# seam L1 invalidate issued early by wave 0 at the start of the barrier preamble (8 seam sites), intermediate drains relaxed to vmcnt(1)
# baseline (speedup 1.0000x reference)
.LBB0_351:
	s_cmp_lg_u32 s33, 0
	s_cbranch_scc1 .Learlyinv_7
	buffer_inv sc1
.Learlyinv_7:
	s_mov_b32 s4, 0x22170
	s_add_i32 s4, s4, 0
	v_mov_b32_e32 v0, s4
	ds_read_b32 v0, v0
	s_waitcnt lgkmcnt(0)
	v_cmp_eq_u32_e32 vcc, 0, v0
	s_cbranch_vccnz .LBB0_370
	s_mov_b64 s[16:17], s[20:21]
	s_mov_b32 s4, 0x22168
	s_add_i32 s4, s4, 0
	v_mov_b32_e32 v0, s4
	s_mov_b32 s4, 0x2216c
	ds_read_b32 v0, v0
	s_add_i32 s4, s4, 0
	s_waitcnt vmcnt(1)
	v_mov_b32_e32 v2, s4
	ds_read_b32 v2, v2
	s_waitcnt lgkmcnt(1)
	v_readfirstlane_b32 s4, v0
	s_lshl_b32 s4, s4, 10
	s_waitcnt lgkmcnt(0)
	v_readfirstlane_b32 s5, v2
	s_lshl_b32 s5, s5, 7
	s_and_b32 s5, s5, 0x380
	s_or_b32 s26, s5, s4
	s_lshl_b64 s[4:5], s[26:27], 2
	s_add_u32 s4, s16, s4
	s_addc_u32 s5, s17, s5
	s_add_u32 s6, s4, 0x10000
	s_addc_u32 s7, s5, 0
	s_mov_b32 s4, -1
	s_mov_b32 s5, s33
	v_mov_b32_e32 v2, 0
	v_mbcnt_lo_u32_b32 v0, s4, 0
	v_mbcnt_hi_u32_b32 v0, s4, v0
	v_lshl_or_b32 v0, s5, 6, v0
	s_waitcnt vmcnt(1)
	s_mov_b64 s[4:5], 0
	v_cmp_eq_u32_e32 vcc, 0, v0
	s_barrier
	s_and_saveexec_b64 s[22:23], vcc
	s_cbranch_execz .LBB0_356
	s_mov_b64 s[24:25], exec
	v_mbcnt_lo_u32_b32 v0, s24, 0
	v_mbcnt_hi_u32_b32 v0, s25, v0
	v_cmp_eq_u32_e64 s[4:5], 0, v0
	s_waitcnt vmcnt(1) expcnt(0) lgkmcnt(0)
	s_and_saveexec_b64 s[40:41], s[4:5]
	s_cbranch_execz .LBB0_355
	s_bcnt1_i32_b64 s4, s[24:25]
	v_mov_b32_e32 v2, s4
	global_atomic_add v2, v1, v2, s[6:7] sc0

.LBB0_640:
	s_nop 0
	v_readlane_b32 s2, v255, 10
	v_readlane_b32 s3, v255, 11
	s_and_b64 s[22:23], s[2:3], s[8:9]
	s_xor_b64 s[16:17], s[22:23], -1
	s_mov_b64 s[2:3], -1
	s_and_b64 vcc, exec, s[16:17]
	s_cbranch_vccz .LBB0_733
	s_cmp_lg_u32 s33, 0
	s_cbranch_scc1 .Learlyinv_6
	buffer_inv sc1
.Learlyinv_6:
	s_mov_b32 s2, 0x22170
	s_add_i32 s2, s2, 0
	v_mov_b32_e32 v0, s2
	ds_read_b32 v0, v0
	s_waitcnt lgkmcnt(0)
	v_cmp_eq_u32_e32 vcc, 0, v0
	s_cbranch_vccnz .LBB0_670
	s_mov_b64 s[48:49], s[20:21]
	s_mov_b32 s2, 0x22168
	s_add_i32 s2, s2, 0
	v_mov_b32_e32 v0, s2
	s_mov_b32 s2, 0x2216c
	ds_read_b32 v0, v0
	s_add_i32 s2, s2, 0
	s_waitcnt vmcnt(1)
	v_mov_b32_e32 v2, s2
	ds_read_b32 v2, v2
	s_waitcnt lgkmcnt(1)
	v_readfirstlane_b32 s2, v0
	s_lshl_b32 s2, s2, 10
	s_waitcnt lgkmcnt(0)
	v_readfirstlane_b32 s3, v2
	s_lshl_b32 s3, s3, 7
	s_and_b32 s3, s3, 0x380
	s_or_b32 s26, s3, s2
	s_lshl_b64 s[2:3], s[26:27], 2
	s_add_u32 s2, s48, s2
	s_addc_u32 s3, s49, s3
	s_add_u32 s46, s2, 0x10000
	s_addc_u32 s47, s3, 0
	s_mov_b32 s2, s33
	s_mov_b32 s3, -1
	v_mov_b32_e32 v2, 0
	v_mbcnt_lo_u32_b32 v0, s3, 0
	v_mbcnt_hi_u32_b32 v0, s3, v0
	v_lshl_or_b32 v0, s2, 6, v0
	s_waitcnt vmcnt(1)
	s_mov_b64 s[2:3], 0
	v_cmp_eq_u32_e32 vcc, 0, v0
	s_barrier
	s_and_saveexec_b64 s[24:25], vcc
	s_cbranch_execz .LBB0_646
	s_mov_b64 s[40:41], exec
	v_mbcnt_lo_u32_b32 v0, s40, 0
	v_mbcnt_hi_u32_b32 v0, s41, v0
	v_cmp_eq_u32_e64 s[2:3], 0, v0
	s_waitcnt vmcnt(1) expcnt(0) lgkmcnt(0)
	s_and_saveexec_b64 s[42:43], s[2:3]
	s_cbranch_execz .LBB0_645
	s_bcnt1_i32_b64 s2, s[40:41]
	v_mov_b32_e32 v2, s2
	global_atomic_add v2, v1, v2, s[46:47] sc0

.LBB0_733:
	s_andn2_b64 vcc, exec, s[2:3]
	s_cbranch_vccnz .LBB0_815
	s_cmp_lg_u32 s33, 0
	s_cbranch_scc1 .Learlyinv_5
	buffer_inv sc1
.Learlyinv_5:
	s_mov_b32 s2, 0x22170
	s_add_i32 s2, s2, 0
	v_mov_b32_e32 v0, s2
	ds_read_b32 v0, v0
	s_waitcnt lgkmcnt(0)
	v_cmp_eq_u32_e32 vcc, 0, v0
	s_cbranch_vccnz .LBB0_753
	s_mov_b64 s[48:49], s[20:21]
	s_mov_b32 s2, 0x22168
	s_add_i32 s2, s2, 0
	v_mov_b32_e32 v0, s2
	ds_read_b32 v0, v0
	s_mov_b32 s4, s33
	s_mov_b32 s5, -1
	s_waitcnt vmcnt(1)
	v_mov_b32_e32 v2, 0
	s_waitcnt lgkmcnt(0)
	v_readfirstlane_b32 s2, v0
	s_lshl_b32 s26, s2, 6
	v_mbcnt_lo_u32_b32 v0, s5, 0
	s_lshl_b64 s[2:3], s[26:27], 2
	v_mbcnt_hi_u32_b32 v0, s5, v0
	s_add_u32 s2, s48, s2
	v_lshl_or_b32 v0, s4, 6, v0
	s_addc_u32 s3, s49, s3
	s_waitcnt vmcnt(1)
	s_add_u32 s46, s2, 0x18000
	s_addc_u32 s47, s3, 0
	v_cmp_eq_u32_e32 vcc, 0, v0
	s_mov_b64 s[2:3], 0
	s_barrier
	s_and_saveexec_b64 s[24:25], vcc
	s_cbranch_execz .LBB0_739
	s_mov_b64 s[40:41], exec
	v_mbcnt_lo_u32_b32 v0, s40, 0
	v_mbcnt_hi_u32_b32 v0, s41, v0
	v_cmp_eq_u32_e64 s[2:3], 0, v0
	s_waitcnt vmcnt(1) expcnt(0) lgkmcnt(0)
	s_and_saveexec_b64 s[42:43], s[2:3]
	s_cbranch_execz .LBB0_738
	s_bcnt1_i32_b64 s2, s[40:41]
	v_mov_b32_e32 v2, s2
	global_atomic_add v2, v1, v2, s[46:47] sc0

.LBB0_991:
	s_xor_b64 s[2:3], s[8:9], -1
	s_andn2_b64 vcc, exec, s[2:3]
	s_cbranch_vccnz .LBB0_1013
	s_cmp_lg_u32 s33, 0
	s_cbranch_scc1 .Learlyinv_4
	buffer_inv sc1
.Learlyinv_4:
	s_mov_b64 s[4:5], s[20:21]
	v_readlane_b32 s2, v255, 16
	s_mov_b32 s6, 0x22174
	s_add_u32 s2, s4, s2
	s_addc_u32 s3, s5, 0
	s_add_i32 s6, s6, 0
	v_mov_b32_e32 v0, s6
	ds_read_b32 v0, v0
	s_add_u32 s76, s2, 0xd00000
	s_addc_u32 s77, s3, 0
	s_waitcnt lgkmcnt(0)
	v_readfirstlane_b32 s37, v0
	s_cmpk_lt_u32 s37, 0x2c0
	s_cselect_b64 s[6:7], -1, 0
	s_cmpk_gt_u32 s37, 0x2bf
	s_cbranch_scc1 .LBB0_994
	s_and_b32 s3, s37, 7
	s_lshr_b32 s2, s37, 3
	s_mulk_i32 s3, 0x58
	s_add_i32 s2, s3, s2
	s_mul_i32 s3, s2, 0xba2f
	s_lshr_b32 s3, s3, 22
	s_mulk_i32 s3, 0x58
	s_sub_i32 s2, s2, s3
	s_lshl_b32 s2, s2, 16
	s_and_b32 s2, s2, 0xfff80000
	s_add_u32 s2, s76, s2
	s_addc_u32 s3, s77, 0
	v_writelane_b32 v255, s2, 32
	s_nop 1
	v_writelane_b32 v255, s3, 33
.LBB0_994:
	s_mov_b32 s2, 0x22170
	s_add_i32 s2, s2, 0
	v_mov_b32_e32 v0, s2
	ds_read_b32 v0, v0
	s_waitcnt lgkmcnt(0)
	v_cmp_eq_u32_e32 vcc, 0, v0
	s_cbranch_vccnz .LBB0_1014
	s_mov_b64 s[10:11], s[20:21]
	s_mov_b32 s2, 0x22168
	s_add_i32 s2, s2, 0
	v_mov_b32_e32 v0, s2
	s_mov_b32 s2, 0x2216c
	ds_read_b32 v0, v0
	s_add_i32 s2, s2, 0
	s_waitcnt vmcnt(1)
	v_mov_b32_e32 v2, s2
	ds_read_b32 v2, v2
	s_waitcnt lgkmcnt(1)
	v_readfirstlane_b32 s2, v0
	s_lshl_b32 s2, s2, 10
	s_waitcnt lgkmcnt(0)
	v_readfirstlane_b32 s3, v2
	s_lshl_b32 s3, s3, 7
	s_and_b32 s3, s3, 0x380
	s_or_b32 s26, s3, s2
	s_lshl_b64 s[2:3], s[26:27], 2
	s_add_u32 s2, s10, s2
	s_addc_u32 s3, s11, s3
	s_add_u32 s8, s2, 0x10000
	s_addc_u32 s9, s3, 0
	s_mov_b32 s2, s33
	s_mov_b32 s3, -1
	v_mov_b32_e32 v2, 0
	v_mbcnt_lo_u32_b32 v0, s3, 0
	v_mbcnt_hi_u32_b32 v0, s3, v0
	v_lshl_or_b32 v0, s2, 6, v0
	s_waitcnt vmcnt(1)
	s_mov_b64 s[2:3], 0
	v_cmp_eq_u32_e32 vcc, 0, v0
	s_barrier
	s_and_saveexec_b64 s[12:13], vcc
	s_cbranch_execz .LBB0_999
	s_mov_b64 s[14:15], exec
	v_mbcnt_lo_u32_b32 v0, s14, 0
	v_mbcnt_hi_u32_b32 v0, s15, v0
	v_cmp_eq_u32_e64 s[2:3], 0, v0
	s_waitcnt vmcnt(1) expcnt(0) lgkmcnt(0)
	s_and_saveexec_b64 s[16:17], s[2:3]
	s_cbranch_execz .LBB0_998
	s_bcnt1_i32_b64 s2, s[14:15]
	v_mov_b32_e32 v2, s2
	global_atomic_add v2, v1, v2, s[8:9] sc0

.Learlyinv_3:
	s_mov_b32 s2, 0x22170
	s_add_i32 s2, s2, 0
	s_waitcnt vmcnt(1)
	v_mov_b32_e32 v0, s2
	ds_read_b32 v0, v0
	s_waitcnt lgkmcnt(0)
	v_cmp_eq_u32_e32 vcc, 0, v0
	s_cbranch_vccnz .LBB0_1233
	s_mov_b64 s[8:9], s[20:21]
	s_mov_b32 s2, 0x22168
	s_add_i32 s2, s2, 0
	v_mov_b32_e32 v0, s2
	ds_read_b32 v0, v0
	s_mov_b32 s2, s33
	s_mov_b32 s3, -1
	s_waitcnt lgkmcnt(0)
	v_readfirstlane_b32 s4, v0
	v_mbcnt_lo_u32_b32 v0, s3, 0
	v_mbcnt_hi_u32_b32 v0, s3, v0
	v_lshl_or_b32 v0, s2, 6, v0
	s_waitcnt vmcnt(1)
	s_nop 0
	v_cmp_eq_u32_e32 vcc, 0, v0
	s_barrier
	s_and_saveexec_b64 s[2:3], vcc
	s_cbranch_execz .LBB0_1238
	s_lshl_b32 s26, s4, 6
	s_lshl_b64 s[4:5], s[26:27], 2
	s_mov_b64 s[6:7], exec
	s_add_u32 s4, s8, s4
	s_addc_u32 s5, s9, s5
	v_mbcnt_lo_u32_b32 v0, s6, 0
	s_add_u32 s4, s4, 0x18000
	v_mbcnt_hi_u32_b32 v0, s7, v0
	s_addc_u32 s5, s5, 0
	v_cmp_eq_u32_e32 vcc, 0, v0
	s_waitcnt vmcnt(1) expcnt(0) lgkmcnt(0)
	s_and_saveexec_b64 s[10:11], vcc
	s_cbranch_execz .LBB0_1223
	s_bcnt1_i32_b64 s6, s[6:7]
	v_mov_b32_e32 v2, s6
	global_atomic_add v2, v1, v2, s[4:5] sc0

.Learlyinv_2:
	s_mov_b64 s[4:5], s[20:21]
	v_readlane_b32 s2, v255, 16
	s_mov_b32 s6, 0x22174
	s_add_u32 s2, s4, s2
	s_addc_u32 s3, s5, 0
	s_add_i32 s6, s6, 0
	v_mov_b32_e32 v0, s6
	ds_read_b32 v0, v0
	s_add_u32 s37, s2, 0x1280000
	s_addc_u32 s64, s3, 0
	s_waitcnt lgkmcnt(0)
	v_readfirstlane_b32 s65, v0
	s_cmpk_lt_u32 s65, 0x100
	s_cselect_b64 s[6:7], -1, 0
	s_lshl_b32 s2, s65, 13
	s_and_b32 s2, s2, 0x180000
	s_add_u32 s8, s37, s2
	s_addc_u32 s9, s64, 0
	s_and_b64 s[2:3], s[6:7], exec
	v_readlane_b32 s2, v255, 34
	v_readlane_b32 s3, v255, 35
	s_cselect_b32 s3, s9, s3
	s_cselect_b32 s2, s8, s2
	v_writelane_b32 v255, s2, 34
	s_nop 1
	v_writelane_b32 v255, s3, 35
	s_mov_b32 s2, 0x22170
	s_add_i32 s2, s2, 0
	v_mov_b32_e32 v0, s2
	ds_read_b32 v0, v0
	s_waitcnt lgkmcnt(0)
	v_cmp_eq_u32_e32 vcc, 0, v0
	s_cbranch_vccnz .LBB0_1504
	s_mov_b64 s[10:11], s[20:21]
	s_mov_b32 s2, 0x22168
	s_add_i32 s2, s2, 0
	v_mov_b32_e32 v0, s2
	ds_read_b32 v0, v0
	s_mov_b32 s12, s33
	s_mov_b32 s13, -1
	v_mov_b32_e32 v2, 0
	s_waitcnt lgkmcnt(0)
	v_readfirstlane_b32 s2, v0
	s_lshl_b32 s26, s2, 6
	v_mbcnt_lo_u32_b32 v0, s13, 0
	s_lshl_b64 s[2:3], s[26:27], 2
	v_mbcnt_hi_u32_b32 v0, s13, v0
	s_add_u32 s2, s10, s2
	v_lshl_or_b32 v0, s12, 6, v0
	s_addc_u32 s3, s11, s3
	s_waitcnt vmcnt(1)
	s_add_u32 s8, s2, 0x18000
	s_addc_u32 s9, s3, 0
	v_cmp_eq_u32_e32 vcc, 0, v0
	s_mov_b64 s[2:3], 0
	s_waitcnt vmcnt(1)
	s_barrier
	s_and_saveexec_b64 s[12:13], vcc
	s_cbranch_execz .LBB0_1490
	s_mov_b64 s[14:15], exec
	v_mbcnt_lo_u32_b32 v0, s14, 0
	v_mbcnt_hi_u32_b32 v0, s15, v0
	v_cmp_eq_u32_e64 s[2:3], 0, v0
	s_waitcnt vmcnt(1) expcnt(0) lgkmcnt(0)
	s_and_saveexec_b64 s[16:17], s[2:3]
	s_cbranch_execz .LBB0_1489
	s_bcnt1_i32_b64 s2, s[14:15]
	v_mov_b32_e32 v2, s2
	global_atomic_add v2, v1, v2, s[8:9] sc0

.LBB0_1594:
	s_mov_b32 s2, 0x22170
	s_add_i32 s2, s2, 0
	v_mov_b32_e32 v0, s2
	ds_read_b32 v0, v0
	s_waitcnt lgkmcnt(0)
	v_cmp_eq_u32_e32 vcc, 0, v0
	s_cbranch_vccnz .LBB0_1613
	s_mov_b64 s[10:11], s[20:21]
	s_mov_b32 s2, 0x22168
	s_add_i32 s2, s2, 0
	v_mov_b32_e32 v0, s2
	s_mov_b32 s2, 0x2216c
	ds_read_b32 v0, v0
	s_add_i32 s2, s2, 0
	v_mov_b32_e32 v2, s2
	ds_read_b32 v2, v2
	s_waitcnt lgkmcnt(0)
	v_readfirstlane_b32 s2, v0
	s_lshl_b32 s2, s2, 10
	v_readfirstlane_b32 s3, v2
	s_lshl_b32 s3, s3, 7
	s_and_b32 s3, s3, 0x380
	s_or_b32 s26, s3, s2
	s_lshl_b64 s[2:3], s[26:27], 2
	s_add_u32 s2, s10, s2
	s_addc_u32 s3, s11, s3
	s_add_u32 s8, s2, 0x10000
	s_addc_u32 s9, s3, 0
	s_mov_b32 s2, s33
	s_mov_b32 s3, -1
	v_mov_b32_e32 v2, 0
	v_mbcnt_lo_u32_b32 v0, s3, 0
	v_mbcnt_hi_u32_b32 v0, s3, v0
	v_lshl_or_b32 v0, s2, 6, v0
	s_waitcnt vmcnt(1)
	s_mov_b64 s[2:3], 0
	v_cmp_eq_u32_e32 vcc, 0, v0
	s_waitcnt vmcnt(1)
	s_barrier
	s_and_saveexec_b64 s[12:13], vcc
	s_cbranch_execz .LBB0_1599
	s_mov_b64 s[14:15], exec
	v_mbcnt_lo_u32_b32 v0, s14, 0
	v_mbcnt_hi_u32_b32 v0, s15, v0
	v_cmp_eq_u32_e64 s[2:3], 0, v0
	s_waitcnt vmcnt(1) expcnt(0) lgkmcnt(0)
	s_and_saveexec_b64 s[16:17], s[2:3]
	s_cbranch_execz .LBB0_1598
	s_bcnt1_i32_b64 s2, s[14:15]
	v_mov_b32_e32 v2, s2
	global_atomic_add v2, v1, v2, s[8:9] sc0

.LBB0_1719:
	s_mov_b32 s2, 0x22170
	s_add_i32 s2, s2, 0
	v_mov_b32_e32 v0, s2
	ds_read_b32 v0, v0
	s_waitcnt lgkmcnt(0)
	v_cmp_eq_u32_e32 vcc, 0, v0
	s_cbranch_vccnz .LBB0_1738
	s_mov_b64 s[12:13], s[20:21]
	s_mov_b32 s2, 0x22168
	s_add_i32 s2, s2, 0
	v_mov_b32_e32 v0, s2
	s_mov_b32 s2, 0x2216c
	ds_read_b32 v0, v0
	s_add_i32 s2, s2, 0
	v_mov_b32_e32 v2, s2
	ds_read_b32 v2, v2
	s_waitcnt lgkmcnt(0)
	v_readfirstlane_b32 s2, v0
	s_lshl_b32 s2, s2, 10
	v_readfirstlane_b32 s3, v2
	s_lshl_b32 s3, s3, 7
	s_and_b32 s3, s3, 0x380
	s_or_b32 s26, s3, s2
	s_lshl_b64 s[2:3], s[26:27], 2
	s_add_u32 s2, s12, s2
	s_addc_u32 s3, s13, s3
	s_add_u32 s6, s2, 0x10000
	s_addc_u32 s7, s3, 0
	s_mov_b32 s2, s33
	s_mov_b32 s3, -1
	v_mov_b32_e32 v2, 0
	v_mbcnt_lo_u32_b32 v0, s3, 0
	v_mbcnt_hi_u32_b32 v0, s3, v0
	v_lshl_or_b32 v0, s2, 6, v0
	s_waitcnt vmcnt(1)
	s_mov_b64 s[2:3], 0
	v_cmp_eq_u32_e32 vcc, 0, v0
	s_waitcnt vmcnt(1)
	s_barrier
	s_and_saveexec_b64 s[14:15], vcc
	s_cbranch_execz .LBB0_1724
	s_mov_b64 s[16:17], exec
	v_mbcnt_lo_u32_b32 v0, s16, 0
	v_mbcnt_hi_u32_b32 v0, s17, v0
	v_cmp_eq_u32_e64 s[2:3], 0, v0
	s_waitcnt vmcnt(1) expcnt(0) lgkmcnt(0)
	s_and_saveexec_b64 s[22:23], s[2:3]
	s_cbranch_execz .LBB0_1723
	s_bcnt1_i32_b64 s2, s[16:17]
	v_mov_b32_e32 v2, s2
	global_atomic_add v2, v1, v2, s[6:7] sc0
